# v42 variant: MLA QK refill ds_read right after every MFMA
# baseline (speedup 1.0000x reference)
.LBB0_2904:
	v_add_u32_e32 v0, s28, v183
	ds_read_b128 v[2:5], v0 offset:24576
	ds_read_b128 v[6:9], v0 offset:28672
	ds_read_b128 v[10:13], v0 offset:32768
	ds_read_b128 v[184:187], v0 offset:36864
	v_exp_f32_e32 v14, v96
	v_exp_f32_e32 v190, v97
	v_exp_f32_e32 v98, v98
	v_exp_f32_e32 v192, v99
	v_exp_f32_e32 v15, v100
	v_exp_f32_e32 v191, v101
	v_exp_f32_e32 v99, v102
	v_exp_f32_e32 v193, v103
	v_add_u32_e32 v0, s28, v182
	v_pk_add_f32 v[96:97], v[14:15], v[190:191]
	v_pk_add_f32 v[100:101], v[98:99], v[192:193]
	s_nop 0
	v_pk_add_f32 v[96:97], v[96:97], v[100:101]
	v_cvt_pk_bf16_f32 v99, v99, v193
	v_pk_add_f32 v[202:203], v[96:97], v[96:97] op_sel_hi:[0,1]
	v_cvt_pk_bf16_f32 v96, v14, v190
	v_cvt_pk_bf16_f32 v97, v98, v192
	v_cvt_pk_bf16_f32 v98, v15, v191
	ds_read_b128 v[100:103], v0 offset:24576
	ds_read_b128 v[190:193], v0 offset:28672
	ds_read_b128 v[194:197], v0 offset:32768
	ds_read_b128 v[198:201], v0 offset:36864
	s_waitcnt lgkmcnt(0)
	v_mfma_f32_32x32x16_bf16 v[64:79], v[2:5], v[96:99], v[64:79]
	v_mfma_f32_32x32x16_bf16 v[48:63], v[6:9], v[96:99], v[48:63]
	v_mfma_f32_32x32x16_bf16 v[32:47], v[10:13], v[96:99], v[32:47]
	v_mfma_f32_32x32x16_bf16 v[16:31], v[184:187], v[96:99], v[16:31]
	v_exp_f32_e32 v2, v104
	v_exp_f32_e32 v4, v105
	v_exp_f32_e32 v3, v106
	v_exp_f32_e32 v5, v107
	v_exp_f32_e32 v6, v108
	v_exp_f32_e32 v8, v109
	v_exp_f32_e32 v7, v110
	v_exp_f32_e32 v9, v111
	v_pk_add_f32 v[10:11], v[2:3], v[4:5]
	v_add_u32_e32 v0, s28, v180
	v_pk_add_f32 v[14:15], v[10:11], v[10:11] op_sel_hi:[0,1]
	v_pk_add_f32 v[10:11], v[6:7], v[8:9]
	v_cvt_pk_bf16_f32 v2, v2, v4
	v_pk_add_f32 v[184:185], v[10:11], v[10:11] op_sel_hi:[0,1]
	v_cvt_pk_bf16_f32 v3, v3, v5
	v_cvt_pk_bf16_f32 v4, v6, v8
	v_cvt_pk_bf16_f32 v5, v7, v9
	ds_read_b128 v[6:9], v0 offset:24576
	ds_read_b128 v[10:13], v0 offset:28672
	ds_read_b128 v[96:99], v0 offset:32768
	ds_read_b128 v[104:107], v0 offset:36864
	v_mfma_f32_32x32x16_bf16 v[64:79], v[100:103], v[2:5], v[64:79]
	v_mfma_f32_32x32x16_bf16 v[48:63], v[190:193], v[2:5], v[48:63]
	v_mfma_f32_32x32x16_bf16 v[32:47], v[194:197], v[2:5], v[32:47]
	v_mfma_f32_32x32x16_bf16 v[16:31], v[198:201], v[2:5], v[16:31]
	v_exp_f32_e32 v0, v80
	v_exp_f32_e32 v2, v81
	v_exp_f32_e32 v3, v82
	v_exp_f32_e32 v4, v83
	v_exp_f32_e32 v5, v84
	v_exp_f32_e32 v14, v85
	v_exp_f32_e32 v80, v86
	v_exp_f32_e32 v81, v87
	v_add_f32_e32 v187, v0, v2
	v_cvt_pk_bf16_f32 v2, v0, v2
	v_add_u32_e32 v0, s28, v175
	v_add_f32_e32 v191, v3, v4
	v_add_f32_e32 v193, v5, v14
	v_add_f32_e32 v195, v80, v81
	v_cvt_pk_bf16_f32 v3, v3, v4
	v_cvt_pk_bf16_f32 v4, v5, v14
	v_cvt_pk_bf16_f32 v5, v80, v81
	ds_read_b128 v[80:83], v0 offset:24576
	ds_read_b128 v[84:87], v0 offset:28672
	ds_read_b128 v[100:103], v0 offset:32768
	ds_read_b128 v[108:111], v0 offset:36864
	s_waitcnt lgkmcnt(0)
	v_mfma_f32_32x32x16_bf16 v[64:79], v[6:9], v[2:5], v[64:79]
	v_mfma_f32_32x32x16_bf16 v[48:63], v[10:13], v[2:5], v[48:63]
	v_mfma_f32_32x32x16_bf16 v[32:47], v[96:99], v[2:5], v[32:47]
	v_mfma_f32_32x32x16_bf16 v[16:31], v[104:107], v[2:5], v[16:31]
	v_exp_f32_e32 v186, v88
	v_exp_f32_e32 v190, v89
	v_exp_f32_e32 v192, v90
	v_exp_f32_e32 v194, v91
	v_exp_f32_e32 v14, v92
	v_exp_f32_e32 v184, v93
	v_exp_f32_e32 v202, v94
	v_exp_f32_e32 v0, v95
	v_cvt_pk_bf16_f32 v2, v186, v190
	v_cvt_pk_bf16_f32 v3, v192, v194
	v_cvt_pk_bf16_f32 v4, v14, v184
	v_cvt_pk_bf16_f32 v5, v202, v0
	s_nop 1
	v_mfma_f32_32x32x16_bf16 v[64:79], v[80:83], v[2:5], v[64:79]
	v_add_f32_e64 v6, v186, v190
	v_add_f32_e64 v7, v187, v191
	v_add_f32_e64 v8, v192, v194
	v_add_f32_e64 v9, v193, v195
	v_add_f32_e64 v10, v202, v0
	v_add_f32_e64 v11, v203, v1
	v_pk_add_f32 v[6:7], v[6:7], v[8:9]
	v_pk_add_f32 v[8:9], v[14:15], v[184:185]
	s_nop 0
	v_pk_add_f32 v[8:9], v[8:9], v[10:11]
	v_mfma_f32_32x32x16_bf16 v[48:63], v[84:87], v[2:5], v[48:63]
	v_add_f32_e64 v6, v6, v8
	v_add_f32_e64 v7, v7, v9
	v_pk_add_f32 v[6:7], v[6:7], v[6:7] op_sel:[0,1] op_sel_hi:[1,0]
	v_mfma_f32_32x32x16_bf16 v[32:47], v[100:103], v[2:5], v[32:47]
	v_mfma_f32_32x32x16_bf16 v[16:31], v[108:111], v[2:5], v[16:31]
	v_mov_b32_e32 v0, v6
	s_nop 1
	v_permlane32_swap_b32_e32 v6, v0
	v_add_f32_e32 v0, v6, v0
	v_add_f32_e32 v171, v171, v0
	v_add_u32_e32 v0, s1, v174
	v_add_u32_e32 v14, s1, v173
	v_add_u32_e32 v15, s1, v170
	ds_read_b128 v[2:5], v0
	ds_read_b128 v[6:9], v0 offset:12288
	ds_read_b128 v[10:13], v14
	ds_read_b128 v[184:187], v14 offset:12288
	v_add_u32_e32 v206, s1, v172
	ds_read_b128 v[190:193], v15
	ds_read_b128 v[194:197], v15 offset:12288
	ds_read_b128 v[198:201], v206
	ds_read_b128 v[202:205], v206 offset:12288
	v_xor_b32_e32 v80, 0x80000000, v181
	v_mov_b32_e32 v81, v80
	v_mov_b32_e32 v82, v80
	v_mov_b32_e32 v83, v80
	v_mov_b32_e32 v84, v80
	v_mov_b32_e32 v85, v80
	v_mov_b32_e32 v86, v80
	v_mov_b32_e32 v87, v80
	v_mov_b32_e32 v88, v80
	v_mov_b32_e32 v89, v80
	v_mov_b32_e32 v90, v80
	v_mov_b32_e32 v91, v80
	v_mov_b32_e32 v92, v80
	v_mov_b32_e32 v93, v80
	v_mov_b32_e32 v94, v80
	v_mov_b32_e32 v95, v80
	s_waitcnt lgkmcnt(0)
	s_nop 0
	v_mfma_f32_32x32x16_bf16 v[96:111], v[2:5], v[112:115], v[80:95]
	ds_read_b128 v[2:5], v14 offset:12416
	v_mfma_f32_32x32x16_bf16 v[96:111], v[10:13], v[116:119], v[96:111]
	ds_read_b128 v[10:13], v0 offset:12416
	v_mfma_f32_32x32x16_bf16 v[80:95], v[6:9], v[112:115], v[80:95]
	ds_read_b128 v[6:9], v14 offset:128
	v_mfma_f32_32x32x16_bf16 v[80:95], v[184:187], v[116:119], v[80:95]
	ds_read_b128 v[184:187], v0 offset:128
	v_mfma_f32_32x32x16_bf16 v[96:111], v[190:193], v[120:123], v[96:111]
	ds_read_b128 v[190:193], v15 offset:128
	v_mfma_f32_32x32x16_bf16 v[96:111], v[198:201], v[124:127], v[96:111]
	ds_read_b128 v[198:201], v206 offset:128
	v_mfma_f32_32x32x16_bf16 v[80:95], v[194:197], v[120:123], v[80:95]
	ds_read_b128 v[194:197], v15 offset:12416
	v_mfma_f32_32x32x16_bf16 v[80:95], v[202:205], v[124:127], v[80:95]
	ds_read_b128 v[202:205], v206 offset:12416
	s_waitcnt lgkmcnt(0)
	v_mfma_f32_32x32x16_bf16 v[96:111], v[184:187], v[128:131], v[96:111]
	ds_read_b128 v[184:187], v0 offset:256
	v_mfma_f32_32x32x16_bf16 v[96:111], v[6:9], v[132:135], v[96:111]
	ds_read_b128 v[6:9], v14 offset:256
	v_mfma_f32_32x32x16_bf16 v[80:95], v[10:13], v[128:131], v[80:95]
	ds_read_b128 v[10:13], v0 offset:12544
	v_mfma_f32_32x32x16_bf16 v[80:95], v[2:5], v[132:135], v[80:95]
	ds_read_b128 v[2:5], v14 offset:12544
	v_mfma_f32_32x32x16_bf16 v[96:111], v[190:193], v[136:139], v[96:111]
	ds_read_b128 v[190:193], v15 offset:256
	v_mfma_f32_32x32x16_bf16 v[96:111], v[198:201], v[140:143], v[96:111]
	ds_read_b128 v[198:201], v206 offset:256
	v_mfma_f32_32x32x16_bf16 v[80:95], v[194:197], v[136:139], v[80:95]
	ds_read_b128 v[194:197], v15 offset:12544
	v_mfma_f32_32x32x16_bf16 v[80:95], v[202:205], v[140:143], v[80:95]
	ds_read_b128 v[202:205], v206 offset:12544
	s_waitcnt lgkmcnt(0)
	v_mfma_f32_32x32x16_bf16 v[96:111], v[184:187], v[144:147], v[96:111]
	v_mfma_f32_32x32x16_bf16 v[96:111], v[6:9], v[148:151], v[96:111]
	v_mfma_f32_32x32x16_bf16 v[80:95], v[10:13], v[144:147], v[80:95]
	v_mfma_f32_32x32x16_bf16 v[80:95], v[2:5], v[148:151], v[80:95]
	v_mfma_f32_32x32x16_bf16 v[96:111], v[190:193], v[152:155], v[96:111]
	v_mfma_f32_32x32x16_bf16 v[96:111], v[198:201], v[156:159], v[96:111]
	v_mfma_f32_32x32x16_bf16 v[80:95], v[194:197], v[152:155], v[80:95]
	s_nop 10
	v_max_f32_e32 v0, v97, v97
	v_max_f32_e32 v2, v96, v96
	v_max_f32_e32 v0, v2, v0
	v_max3_f32 v0, v0, v98, v99
	v_max3_f32 v0, v0, v100, v101
	v_max3_f32 v0, v0, v102, v103
	v_max3_f32 v0, v0, v104, v105
	v_mfma_f32_32x32x16_bf16 v[80:95], v[202:205], v[156:159], v[80:95]
	v_max3_f32 v0, v0, v106, v107
	v_max3_f32 v0, v0, v108, v109
	v_max3_f32 v0, v0, v110, v111
	s_mov_b32 s28, 0x41000000
	s_nop 7
	v_max3_f32 v0, v0, v80, v81
	v_max3_f32 v0, v0, v82, v83
	v_max3_f32 v0, v0, v84, v85
	v_max3_f32 v0, v0, v86, v87
	v_max3_f32 v0, v0, v88, v89
	v_max3_f32 v0, v0, v90, v91
	v_max3_f32 v0, v0, v92, v93
	v_max3_f32 v0, v0, v94, v95
	v_mov_b32_e32 v2, v0
	s_nop 1
	v_permlane32_swap_b32_e32 v0, v2
	v_max_f32_e32 v2, v2, v2
	v_max_f32_e32 v0, v0, v0
	v_max_f32_e32 v0, v0, v2
	v_cmp_ge_f32_e32 vcc, s28, v0
	s_cmp_eq_u64 vcc, exec
	s_cbranch_scc1 .LBB0_2906
	v_max_f32_e32 v0, v0, v0
	v_max_f32_e32 v2, 0, v0
	v_exp_f32_e64 v0, -v2
	v_add_f32_e32 v181, v181, v2
	v_sub_f32_e32 v111, v111, v2
	v_sub_f32_e32 v110, v110, v2
	v_pk_mul_f32 v[78:79], v[78:79], v[0:1] op_sel_hi:[1,0]
	v_pk_mul_f32 v[76:77], v[76:77], v[0:1] op_sel_hi:[1,0]
	v_pk_mul_f32 v[74:75], v[74:75], v[0:1] op_sel_hi:[1,0]
	v_pk_mul_f32 v[72:73], v[72:73], v[0:1] op_sel_hi:[1,0]
	v_pk_mul_f32 v[70:71], v[70:71], v[0:1] op_sel_hi:[1,0]
	v_pk_mul_f32 v[68:69], v[68:69], v[0:1] op_sel_hi:[1,0]
	v_pk_mul_f32 v[66:67], v[66:67], v[0:1] op_sel_hi:[1,0]
	v_pk_mul_f32 v[64:65], v[64:65], v[0:1] op_sel_hi:[1,0]
	v_pk_mul_f32 v[62:63], v[62:63], v[0:1] op_sel_hi:[1,0]
	v_pk_mul_f32 v[60:61], v[60:61], v[0:1] op_sel_hi:[1,0]
	v_pk_mul_f32 v[58:59], v[58:59], v[0:1] op_sel_hi:[1,0]
	v_pk_mul_f32 v[56:57], v[56:57], v[0:1] op_sel_hi:[1,0]
	v_pk_mul_f32 v[54:55], v[54:55], v[0:1] op_sel_hi:[1,0]
	v_pk_mul_f32 v[52:53], v[52:53], v[0:1] op_sel_hi:[1,0]
	v_pk_mul_f32 v[50:51], v[50:51], v[0:1] op_sel_hi:[1,0]
	v_pk_mul_f32 v[48:49], v[48:49], v[0:1] op_sel_hi:[1,0]
	v_pk_mul_f32 v[46:47], v[46:47], v[0:1] op_sel_hi:[1,0]
	v_pk_mul_f32 v[44:45], v[44:45], v[0:1] op_sel_hi:[1,0]
	v_pk_mul_f32 v[42:43], v[42:43], v[0:1] op_sel_hi:[1,0]
	v_pk_mul_f32 v[40:41], v[40:41], v[0:1] op_sel_hi:[1,0]
	v_pk_mul_f32 v[38:39], v[38:39], v[0:1] op_sel_hi:[1,0]
	v_pk_mul_f32 v[36:37], v[36:37], v[0:1] op_sel_hi:[1,0]
	v_pk_mul_f32 v[34:35], v[34:35], v[0:1] op_sel_hi:[1,0]
	v_pk_mul_f32 v[32:33], v[32:33], v[0:1] op_sel_hi:[1,0]
	v_pk_mul_f32 v[30:31], v[30:31], v[0:1] op_sel_hi:[1,0]
	v_pk_mul_f32 v[28:29], v[28:29], v[0:1] op_sel_hi:[1,0]
	v_pk_mul_f32 v[26:27], v[26:27], v[0:1] op_sel_hi:[1,0]
	v_pk_mul_f32 v[24:25], v[24:25], v[0:1] op_sel_hi:[1,0]
	v_pk_mul_f32 v[22:23], v[22:23], v[0:1] op_sel_hi:[1,0]
	v_pk_mul_f32 v[20:21], v[20:21], v[0:1] op_sel_hi:[1,0]
	v_pk_mul_f32 v[18:19], v[18:19], v[0:1] op_sel_hi:[1,0]
	v_pk_mul_f32 v[16:17], v[16:17], v[0:1] op_sel_hi:[1,0]
	v_sub_f32_e32 v109, v109, v2
	v_sub_f32_e32 v108, v108, v2
	v_sub_f32_e32 v107, v107, v2
	v_sub_f32_e32 v106, v106, v2
	v_sub_f32_e32 v105, v105, v2
	v_sub_f32_e32 v104, v104, v2
	v_sub_f32_e32 v103, v103, v2
	v_sub_f32_e32 v102, v102, v2
	v_sub_f32_e32 v101, v101, v2
	v_sub_f32_e32 v100, v100, v2
	v_sub_f32_e32 v99, v99, v2
	v_sub_f32_e32 v98, v98, v2
	v_sub_f32_e32 v97, v97, v2
	v_sub_f32_e32 v96, v96, v2
	v_sub_f32_e32 v95, v95, v2
	v_sub_f32_e32 v94, v94, v2
	v_sub_f32_e32 v93, v93, v2
	v_sub_f32_e32 v92, v92, v2
	v_sub_f32_e32 v91, v91, v2
	v_sub_f32_e32 v90, v90, v2
	v_sub_f32_e32 v89, v89, v2
	v_sub_f32_e32 v88, v88, v2
	v_sub_f32_e32 v87, v87, v2
	v_sub_f32_e32 v86, v86, v2
	v_sub_f32_e32 v85, v85, v2
	v_sub_f32_e32 v84, v84, v2
	v_sub_f32_e32 v83, v83, v2
	v_sub_f32_e32 v82, v82, v2
	v_sub_f32_e32 v81, v81, v2
	v_sub_f32_e32 v80, v80, v2
	v_mul_f32_e32 v171, v171, v0
